# skinny GEMM row split extended to G5 (own-row normalisation, 128-arrival counter)
# speedup vs baseline: 1.0088x; 1.0019x over previous
.LBB0_1668:
	s_and_b64 vcc, exec, s[0:1]
	s_cbranch_vccz .LBB0_1744
	v_readlane_b32 s0, v255, 3
	v_readlane_b32 s1, v255, 4
	s_load_dwordx2 s[2:3], s[0:1], 0xd0
	s_load_dwordx4 s[12:15], s[0:1], 0xc0
	v_mov_b32_e32 v2, v0
	s_waitcnt lgkmcnt(0)
	s_add_u32 s16, s2, 0x7300000
	s_addc_u32 s17, s3, 0
	s_add_u32 s40, s2, 0x4a00000
	s_addc_u32 s41, s3, 0
	s_and_b64 vcc, exec, s[6:7]
	v_readfirstlane_b32 s0, v2
	s_cbranch_vccnz .LBB0_1677
	s_ashr_i32 s8, s0, 6
	s_ashr_i32 s0, s0, 3
	s_movk_i32 s1, 0xffe0
	v_mov_b32_e32 v4, s0
	v_bfi_b32 v4, s1, v4, v2
	v_ashrrev_i32_e32 v5, 31, v4
	v_lshlrev_b64 v[4:5], 12, v[4:5]
	s_lshl_b32 s0, s8, 10
	v_bfe_u32 v3, v2, 5, 1
	v_lshl_add_u64 v[4:5], s[2:3], 0, v[4:5]
	s_and_b32 s10, s0, 0xc00
	s_mov_b32 s11, 0
	v_lshl_add_u64 v[4:5], v[4:5], 0, s[10:11]
	v_lshlrev_b32_e32 v18, 4, v3
	v_mov_b32_e32 v19, 0
	v_lshl_add_u64 v[4:5], v[4:5], 0, v[18:19]
	s_mov_b64 s[0:1], 0xd500000
	v_lshl_add_u64 v[20:21], v[4:5], 0, s[0:1]
	s_add_u32 s0, s40, s10
	s_addc_u32 s1, s41, 0
	v_lshl_add_u64 v[22:23], s[0:1], 0, v[18:19]
	s_lshl_b32 s0, s8, 5
	v_lshl_or_b32 v8, v3, 2, s0
	s_movk_i32 s0, 0x100
	v_and_b32_e32 v32, 31, v2
	v_lshrrev_b32_e32 v220, 7, v2
	s_and_b32 s66, s94, 1
	v_cmp_eq_u32_e64 s[0:1], s66, v220
	v_ashrrev_i32_e32 v4, 2, v2
	v_and_b32_e32 v5, 3, v2
	v_and_b32_e32 v2, 0x3fffff80, v2
	v_and_or_b32 v10, v4, 31, v2
	v_lshl_add_u32 v11, v5, 5, 0
	v_lshlrev_b32_e32 v33, 3, v5
	v_add_u32_e32 v2, 0x2000, v4
	v_cmp_eq_u32_e64 s[8:9], 0, v5
	v_ashrrev_i32_e32 v5, 31, v4
	v_ashrrev_i32_e32 v3, 31, v2
	v_lshl_add_u64 v[4:5], v[4:5], 2, s[2:3]
	s_mov_b64 s[18:19], 0x28000
	s_movk_i32 s10, 0x84
	v_lshl_add_u32 v9, v32, 2, 0
	v_lshlrev_b64 v[6:7], 12, v[2:3]
	v_lshlrev_b64 v[2:3], 13, v[2:3]
	v_lshl_add_u64 v[24:25], v[4:5], 0, s[18:19]
	v_mul_lo_u32 v4, v8, s10
	v_mul_lo_u32 v5, v10, s10
	v_lshl_add_u64 v[26:27], s[16:17], 0, v[6:7]
	v_lshl_add_u64 v[28:29], s[14:15], 0, v[2:3]
	v_add_u32_e32 v34, v9, v4
	v_add_u32_e32 v35, v11, v5
	v_mbcnt_hi_u32_b32 v36, -1, v1
	s_lshr_b32 s22, s94, 1
	s_branch .LBB0_1672

.LBB0_1672:
	s_lshl_b32 s20, s22, 5
	v_or_b32_e32 v2, s20, v32
	v_ashrrev_i32_e32 v3, 31, v2
	v_lshlrev_b64 v[2:3], 12, v[2:3]
	v_lshl_add_u64 v[30:31], v[22:23], 0, v[2:3]
	s_mov_b64 s[18:19], -1
	s_mov_b32 s10, s11
	v_mov_b32_e32 v2, 0
	v_mov_b32_e32 v3, v19
	v_mov_b32_e32 v4, v19
	v_mov_b32_e32 v5, v19
	v_mov_b32_e32 v6, v19
	v_mov_b32_e32 v7, v19
	v_mov_b32_e32 v8, v19
	v_mov_b32_e32 v9, v19
	v_mov_b32_e32 v10, v19
	v_mov_b32_e32 v11, v19
	v_mov_b32_e32 v12, v19
	v_mov_b32_e32 v13, v19
	v_mov_b32_e32 v14, v19
	v_mov_b32_e32 v15, v19
	v_mov_b32_e32 v16, v19
	v_mov_b32_e32 v17, v19
	v_readfirstlane_b32 s66, v20
	v_readfirstlane_b32 s67, v21
	v_readfirstlane_b32 s68, v30
	v_readfirstlane_b32 s69, v31
	v_readfirstlane_b32 s70, v0
	v_mbcnt_lo_u32_b32 v220, -1, 0
	v_mbcnt_hi_u32_b32 v220, -1, v220
	s_lshr_b32 s70, s70, 6
	s_lshr_b32 s71, s70, 2
	s_and_b32 s74, s94, 1
	s_cmp_lg_u32 s71, s74
	s_cbranch_scc1 .Lsk3_end_4
	s_mul_i32 s70, s70, 9216
	s_add_i32 s70, s70, 36864
	v_lshrrev_b32_e32 v221, 3, v220
	v_and_b32_e32 v222, 7, v220
	v_lshlrev_b32_e32 v224, 12, v221
	v_lshl_add_u32 v224, v222, 4, v224
	v_mul_u32_u24_e32 v225, 144, v221
	v_lshl_add_u32 v225, v222, 4, v225
	v_add_u32_e32 v225, s70, v225
	v_and_b32_e32 v221, 31, v220
	v_lshrrev_b32_e32 v222, 5, v220
	v_mul_u32_u24_e32 v226, 144, v221
	v_lshl_add_u32 v226, v222, 4, v226
	v_add_u32_e32 v226, s70, v226
	s_add_u32 s72, s66, 0
	s_addc_u32 s73, s67, 0
	s_add_u32 s74, s68, 0
	s_addc_u32 s75, s69, 0
	global_load_dwordx4 v[106:109], v224, s[72:73]
	global_load_dwordx4 v[122:125], v224, s[74:75]
	s_add_u32 s72, s66, 32768
	s_addc_u32 s73, s67, 0
	s_add_u32 s74, s68, 32768
	s_addc_u32 s75, s69, 0
	global_load_dwordx4 v[110:113], v224, s[72:73]
	global_load_dwordx4 v[126:129], v224, s[74:75]
	s_add_u32 s72, s66, 65536
	s_addc_u32 s73, s67, 0
	s_add_u32 s74, s68, 65536
	s_addc_u32 s75, s69, 0
	global_load_dwordx4 v[114:117], v224, s[72:73]
	global_load_dwordx4 v[130:133], v224, s[74:75]
	s_add_u32 s72, s66, 98304
	s_addc_u32 s73, s67, 0
	s_add_u32 s74, s68, 98304
	s_addc_u32 s75, s69, 0
	global_load_dwordx4 v[118:121], v224, s[72:73]
	global_load_dwordx4 v[134:137], v224, s[74:75]
	s_add_u32 s72, s66, 128
	s_addc_u32 s73, s67, 0
	s_add_u32 s74, s68, 128
	s_addc_u32 s75, s69, 0
	global_load_dwordx4 v[138:141], v224, s[72:73]
	global_load_dwordx4 v[172:175], v224, s[74:75]
	s_add_u32 s72, s66, 32896
	s_addc_u32 s73, s67, 0
	s_add_u32 s74, s68, 32896
	s_addc_u32 s75, s69, 0
	global_load_dwordx4 v[142:145], v224, s[72:73]
	global_load_dwordx4 v[176:179], v224, s[74:75]
	s_add_u32 s72, s66, 65664
	s_addc_u32 s73, s67, 0
	s_add_u32 s74, s68, 65664
	s_addc_u32 s75, s69, 0
	global_load_dwordx4 v[146:149], v224, s[72:73]
	global_load_dwordx4 v[180:183], v224, s[74:75]
	s_add_u32 s72, s66, 98432
	s_addc_u32 s73, s67, 0
	s_add_u32 s74, s68, 98432
	s_addc_u32 s75, s69, 0
	global_load_dwordx4 v[168:171], v224, s[72:73]
	global_load_dwordx4 v[184:187], v224, s[74:75]
	s_add_u32 s72, s66, 256
	s_addc_u32 s73, s67, 0
	s_add_u32 s74, s68, 256
	s_addc_u32 s75, s69, 0
	global_load_dwordx4 v[188:191], v224, s[72:73]
	global_load_dwordx4 v[204:207], v224, s[74:75]
	s_add_u32 s72, s66, 33024
	s_addc_u32 s73, s67, 0
	s_add_u32 s74, s68, 33024
	s_addc_u32 s75, s69, 0
	global_load_dwordx4 v[192:195], v224, s[72:73]
	global_load_dwordx4 v[208:211], v224, s[74:75]
	s_add_u32 s72, s66, 65792
	s_addc_u32 s73, s67, 0
	s_add_u32 s74, s68, 65792
	s_addc_u32 s75, s69, 0
	global_load_dwordx4 v[196:199], v224, s[72:73]
	global_load_dwordx4 v[212:215], v224, s[74:75]
	s_add_u32 s72, s66, 98560
	s_addc_u32 s73, s67, 0
	s_add_u32 s74, s68, 98560
	s_addc_u32 s75, s69, 0
	global_load_dwordx4 v[200:203], v224, s[72:73]
	global_load_dwordx4 v[216:219], v224, s[74:75]
	s_add_u32 s72, s66, 384
	s_addc_u32 s73, s67, 0
	s_add_u32 s74, s68, 384
	s_addc_u32 s75, s69, 0
	global_load_dwordx4 v[228:231], v224, s[72:73]
	global_load_dwordx4 v[244:247], v224, s[74:75]
	s_add_u32 s72, s66, 33152
	s_addc_u32 s73, s67, 0
	s_add_u32 s74, s68, 33152
	s_addc_u32 s75, s69, 0
	global_load_dwordx4 v[232:235], v224, s[72:73]
	global_load_dwordx4 v[248:251], v224, s[74:75]
	s_add_u32 s72, s66, 65920
	s_addc_u32 s73, s67, 0
	s_add_u32 s74, s68, 65920
	s_addc_u32 s75, s69, 0
	global_load_dwordx4 v[236:239], v224, s[72:73]
	global_load_dwordx4 v[52:55], v224, s[74:75]
	s_add_u32 s72, s66, 98688
	s_addc_u32 s73, s67, 0
	s_add_u32 s74, s68, 98688
	s_addc_u32 s75, s69, 0
	global_load_dwordx4 v[240:243], v224, s[72:73]
	global_load_dwordx4 v[56:59], v224, s[74:75]
	s_waitcnt vmcnt(24)
	ds_write_b128 v225, v[106:109]
	ds_write_b128 v225, v[110:113] offset:1152
	ds_write_b128 v225, v[114:117] offset:2304
	ds_write_b128 v225, v[118:121] offset:3456
	ds_write_b128 v225, v[122:125] offset:4608
	ds_write_b128 v225, v[126:129] offset:5760
	ds_write_b128 v225, v[130:133] offset:6912
	ds_write_b128 v225, v[134:137] offset:8064
	s_nop 1
	s_add_u32 s72, s66, 512
	s_addc_u32 s73, s67, 0
	s_add_u32 s74, s68, 512
	s_addc_u32 s75, s69, 0
	global_load_dwordx4 v[106:109], v224, s[72:73]
	global_load_dwordx4 v[122:125], v224, s[74:75]
	s_add_u32 s72, s66, 33280
	s_addc_u32 s73, s67, 0
	s_add_u32 s74, s68, 33280
	s_addc_u32 s75, s69, 0
	global_load_dwordx4 v[110:113], v224, s[72:73]
	global_load_dwordx4 v[126:129], v224, s[74:75]
	s_add_u32 s72, s66, 66048
	s_addc_u32 s73, s67, 0
	s_add_u32 s74, s68, 66048
	s_addc_u32 s75, s69, 0
	global_load_dwordx4 v[114:117], v224, s[72:73]
	global_load_dwordx4 v[130:133], v224, s[74:75]
	s_add_u32 s72, s66, 98816
	s_addc_u32 s73, s67, 0
	s_add_u32 s74, s68, 98816
	s_addc_u32 s75, s69, 0
	global_load_dwordx4 v[118:121], v224, s[72:73]
	global_load_dwordx4 v[134:137], v224, s[74:75]
	s_waitcnt lgkmcnt(0)
	ds_read_b128 v[60:63], v226
	ds_read_b128 v[64:67], v226 offset:4608
	ds_read_b128 v[68:71], v226 offset:32
	ds_read_b128 v[80:83], v226 offset:4640
	ds_read_b128 v[88:91], v226 offset:64
	ds_read_b128 v[92:95], v226 offset:4672
	ds_read_b128 v[96:99], v226 offset:96
	ds_read_b128 v[100:103], v226 offset:4704
	s_waitcnt lgkmcnt(6)
	v_mfma_f32_32x32x16_bf16 v[2:17], v[60:63], v[64:67], v[2:17]
	s_waitcnt lgkmcnt(4)
	v_mfma_f32_32x32x16_bf16 v[2:17], v[68:71], v[80:83], v[2:17]
	s_waitcnt lgkmcnt(2)
	v_mfma_f32_32x32x16_bf16 v[2:17], v[88:91], v[92:95], v[2:17]
	s_waitcnt lgkmcnt(0)
	v_mfma_f32_32x32x16_bf16 v[2:17], v[96:99], v[100:103], v[2:17]
	s_waitcnt vmcnt(24)
	ds_write_b128 v225, v[138:141]
	ds_write_b128 v225, v[142:145] offset:1152
	ds_write_b128 v225, v[146:149] offset:2304
	ds_write_b128 v225, v[168:171] offset:3456
	ds_write_b128 v225, v[172:175] offset:4608
	ds_write_b128 v225, v[176:179] offset:5760
	ds_write_b128 v225, v[180:183] offset:6912
	ds_write_b128 v225, v[184:187] offset:8064
	s_nop 1
	s_add_u32 s72, s66, 640
	s_addc_u32 s73, s67, 0
	s_add_u32 s74, s68, 640
	s_addc_u32 s75, s69, 0
	global_load_dwordx4 v[138:141], v224, s[72:73]
	global_load_dwordx4 v[172:175], v224, s[74:75]
	s_add_u32 s72, s66, 33408
	s_addc_u32 s73, s67, 0
	s_add_u32 s74, s68, 33408
	s_addc_u32 s75, s69, 0
	global_load_dwordx4 v[142:145], v224, s[72:73]
	global_load_dwordx4 v[176:179], v224, s[74:75]
	s_add_u32 s72, s66, 66176
	s_addc_u32 s73, s67, 0
	s_add_u32 s74, s68, 66176
	s_addc_u32 s75, s69, 0
	global_load_dwordx4 v[146:149], v224, s[72:73]
	global_load_dwordx4 v[180:183], v224, s[74:75]
	s_add_u32 s72, s66, 98944
	s_addc_u32 s73, s67, 0
	s_add_u32 s74, s68, 98944
	s_addc_u32 s75, s69, 0
	global_load_dwordx4 v[168:171], v224, s[72:73]
	global_load_dwordx4 v[184:187], v224, s[74:75]
	s_waitcnt lgkmcnt(0)
	ds_read_b128 v[60:63], v226
	ds_read_b128 v[64:67], v226 offset:4608
	ds_read_b128 v[68:71], v226 offset:32
	ds_read_b128 v[80:83], v226 offset:4640
	ds_read_b128 v[88:91], v226 offset:64
	ds_read_b128 v[92:95], v226 offset:4672
	ds_read_b128 v[96:99], v226 offset:96
	ds_read_b128 v[100:103], v226 offset:4704
	s_waitcnt lgkmcnt(6)
	v_mfma_f32_32x32x16_bf16 v[2:17], v[60:63], v[64:67], v[2:17]
	s_waitcnt lgkmcnt(4)
	v_mfma_f32_32x32x16_bf16 v[2:17], v[68:71], v[80:83], v[2:17]
	s_waitcnt lgkmcnt(2)
	v_mfma_f32_32x32x16_bf16 v[2:17], v[88:91], v[92:95], v[2:17]
	s_waitcnt lgkmcnt(0)
	v_mfma_f32_32x32x16_bf16 v[2:17], v[96:99], v[100:103], v[2:17]
	s_waitcnt vmcnt(24)
	ds_write_b128 v225, v[188:191]
	ds_write_b128 v225, v[192:195] offset:1152
	ds_write_b128 v225, v[196:199] offset:2304
	ds_write_b128 v225, v[200:203] offset:3456
	ds_write_b128 v225, v[204:207] offset:4608
	ds_write_b128 v225, v[208:211] offset:5760
	ds_write_b128 v225, v[212:215] offset:6912
	ds_write_b128 v225, v[216:219] offset:8064
	s_nop 1
	s_add_u32 s72, s66, 768
	s_addc_u32 s73, s67, 0
	s_add_u32 s74, s68, 768
	s_addc_u32 s75, s69, 0
	global_load_dwordx4 v[188:191], v224, s[72:73]
	global_load_dwordx4 v[204:207], v224, s[74:75]
	s_add_u32 s72, s66, 33536
	s_addc_u32 s73, s67, 0
	s_add_u32 s74, s68, 33536
	s_addc_u32 s75, s69, 0
	global_load_dwordx4 v[192:195], v224, s[72:73]
	global_load_dwordx4 v[208:211], v224, s[74:75]
	s_add_u32 s72, s66, 66304
	s_addc_u32 s73, s67, 0
	s_add_u32 s74, s68, 66304
	s_addc_u32 s75, s69, 0
	global_load_dwordx4 v[196:199], v224, s[72:73]
	global_load_dwordx4 v[212:215], v224, s[74:75]
	s_add_u32 s72, s66, 99072
	s_addc_u32 s73, s67, 0
	s_add_u32 s74, s68, 99072
	s_addc_u32 s75, s69, 0
	global_load_dwordx4 v[200:203], v224, s[72:73]
	global_load_dwordx4 v[216:219], v224, s[74:75]
	s_waitcnt lgkmcnt(0)
	ds_read_b128 v[60:63], v226
	ds_read_b128 v[64:67], v226 offset:4608
	ds_read_b128 v[68:71], v226 offset:32
	ds_read_b128 v[80:83], v226 offset:4640
	ds_read_b128 v[88:91], v226 offset:64
	ds_read_b128 v[92:95], v226 offset:4672
	ds_read_b128 v[96:99], v226 offset:96
	ds_read_b128 v[100:103], v226 offset:4704
	s_waitcnt lgkmcnt(6)
	v_mfma_f32_32x32x16_bf16 v[2:17], v[60:63], v[64:67], v[2:17]
	s_waitcnt lgkmcnt(4)
	v_mfma_f32_32x32x16_bf16 v[2:17], v[68:71], v[80:83], v[2:17]
	s_waitcnt lgkmcnt(2)
	v_mfma_f32_32x32x16_bf16 v[2:17], v[88:91], v[92:95], v[2:17]
	s_waitcnt lgkmcnt(0)
	v_mfma_f32_32x32x16_bf16 v[2:17], v[96:99], v[100:103], v[2:17]
	s_waitcnt vmcnt(24)
	ds_write_b128 v225, v[228:231]
	ds_write_b128 v225, v[232:235] offset:1152
	ds_write_b128 v225, v[236:239] offset:2304
	ds_write_b128 v225, v[240:243] offset:3456
	ds_write_b128 v225, v[244:247] offset:4608
	ds_write_b128 v225, v[248:251] offset:5760
	ds_write_b128 v225, v[52:55] offset:6912
	ds_write_b128 v225, v[56:59] offset:8064
	s_nop 1
	s_add_u32 s72, s66, 896
	s_addc_u32 s73, s67, 0
	s_add_u32 s74, s68, 896
	s_addc_u32 s75, s69, 0
	global_load_dwordx4 v[228:231], v224, s[72:73]
	global_load_dwordx4 v[244:247], v224, s[74:75]
	s_add_u32 s72, s66, 33664
	s_addc_u32 s73, s67, 0
	s_add_u32 s74, s68, 33664
	s_addc_u32 s75, s69, 0
	global_load_dwordx4 v[232:235], v224, s[72:73]
	global_load_dwordx4 v[248:251], v224, s[74:75]
	s_add_u32 s72, s66, 66432
	s_addc_u32 s73, s67, 0
	s_add_u32 s74, s68, 66432
	s_addc_u32 s75, s69, 0
	global_load_dwordx4 v[236:239], v224, s[72:73]
	global_load_dwordx4 v[52:55], v224, s[74:75]
	s_add_u32 s72, s66, 99200
	s_addc_u32 s73, s67, 0
	s_add_u32 s74, s68, 99200
	s_addc_u32 s75, s69, 0
	global_load_dwordx4 v[240:243], v224, s[72:73]
	global_load_dwordx4 v[56:59], v224, s[74:75]
	s_waitcnt lgkmcnt(0)
	ds_read_b128 v[60:63], v226
	ds_read_b128 v[64:67], v226 offset:4608
	ds_read_b128 v[68:71], v226 offset:32
	ds_read_b128 v[80:83], v226 offset:4640
	ds_read_b128 v[88:91], v226 offset:64
	ds_read_b128 v[92:95], v226 offset:4672
	ds_read_b128 v[96:99], v226 offset:96
	ds_read_b128 v[100:103], v226 offset:4704
	s_waitcnt lgkmcnt(6)
	v_mfma_f32_32x32x16_bf16 v[2:17], v[60:63], v[64:67], v[2:17]
	s_waitcnt lgkmcnt(4)
	v_mfma_f32_32x32x16_bf16 v[2:17], v[68:71], v[80:83], v[2:17]
	s_waitcnt lgkmcnt(2)
	v_mfma_f32_32x32x16_bf16 v[2:17], v[88:91], v[92:95], v[2:17]
	s_waitcnt lgkmcnt(0)
	v_mfma_f32_32x32x16_bf16 v[2:17], v[96:99], v[100:103], v[2:17]
	s_waitcnt vmcnt(24)
	ds_write_b128 v225, v[106:109]
	ds_write_b128 v225, v[110:113] offset:1152
	ds_write_b128 v225, v[114:117] offset:2304
	ds_write_b128 v225, v[118:121] offset:3456
	ds_write_b128 v225, v[122:125] offset:4608
	ds_write_b128 v225, v[126:129] offset:5760
	ds_write_b128 v225, v[130:133] offset:6912
	ds_write_b128 v225, v[134:137] offset:8064
	s_waitcnt lgkmcnt(0)
	ds_read_b128 v[60:63], v226
	ds_read_b128 v[64:67], v226 offset:4608
	ds_read_b128 v[68:71], v226 offset:32
	ds_read_b128 v[80:83], v226 offset:4640
	ds_read_b128 v[88:91], v226 offset:64
	ds_read_b128 v[92:95], v226 offset:4672
	ds_read_b128 v[96:99], v226 offset:96
	ds_read_b128 v[100:103], v226 offset:4704
	s_waitcnt lgkmcnt(6)
	v_mfma_f32_32x32x16_bf16 v[2:17], v[60:63], v[64:67], v[2:17]
	s_waitcnt lgkmcnt(4)
	v_mfma_f32_32x32x16_bf16 v[2:17], v[68:71], v[80:83], v[2:17]
	s_waitcnt lgkmcnt(2)
	v_mfma_f32_32x32x16_bf16 v[2:17], v[88:91], v[92:95], v[2:17]
	s_waitcnt lgkmcnt(0)
	v_mfma_f32_32x32x16_bf16 v[2:17], v[96:99], v[100:103], v[2:17]
	s_waitcnt vmcnt(16)
	ds_write_b128 v225, v[138:141]
	ds_write_b128 v225, v[142:145] offset:1152
	ds_write_b128 v225, v[146:149] offset:2304
	ds_write_b128 v225, v[168:171] offset:3456
	ds_write_b128 v225, v[172:175] offset:4608
	ds_write_b128 v225, v[176:179] offset:5760
	ds_write_b128 v225, v[180:183] offset:6912
	ds_write_b128 v225, v[184:187] offset:8064
	s_waitcnt lgkmcnt(0)
	ds_read_b128 v[60:63], v226
	ds_read_b128 v[64:67], v226 offset:4608
	ds_read_b128 v[68:71], v226 offset:32
	ds_read_b128 v[80:83], v226 offset:4640
	ds_read_b128 v[88:91], v226 offset:64
	ds_read_b128 v[92:95], v226 offset:4672
	ds_read_b128 v[96:99], v226 offset:96
	ds_read_b128 v[100:103], v226 offset:4704
	s_waitcnt lgkmcnt(6)
	v_mfma_f32_32x32x16_bf16 v[2:17], v[60:63], v[64:67], v[2:17]
	s_waitcnt lgkmcnt(4)
	v_mfma_f32_32x32x16_bf16 v[2:17], v[68:71], v[80:83], v[2:17]
	s_waitcnt lgkmcnt(2)
	v_mfma_f32_32x32x16_bf16 v[2:17], v[88:91], v[92:95], v[2:17]
	s_waitcnt lgkmcnt(0)
	v_mfma_f32_32x32x16_bf16 v[2:17], v[96:99], v[100:103], v[2:17]
	s_waitcnt vmcnt(8)
	ds_write_b128 v225, v[188:191]
	ds_write_b128 v225, v[192:195] offset:1152
	ds_write_b128 v225, v[196:199] offset:2304
	ds_write_b128 v225, v[200:203] offset:3456
	ds_write_b128 v225, v[204:207] offset:4608
	ds_write_b128 v225, v[208:211] offset:5760
	ds_write_b128 v225, v[212:215] offset:6912
	ds_write_b128 v225, v[216:219] offset:8064
	s_waitcnt lgkmcnt(0)
	ds_read_b128 v[60:63], v226
	ds_read_b128 v[64:67], v226 offset:4608
	ds_read_b128 v[68:71], v226 offset:32
	ds_read_b128 v[80:83], v226 offset:4640
	ds_read_b128 v[88:91], v226 offset:64
	ds_read_b128 v[92:95], v226 offset:4672
	ds_read_b128 v[96:99], v226 offset:96
	ds_read_b128 v[100:103], v226 offset:4704
	s_waitcnt lgkmcnt(6)
	v_mfma_f32_32x32x16_bf16 v[2:17], v[60:63], v[64:67], v[2:17]
	s_waitcnt lgkmcnt(4)
	v_mfma_f32_32x32x16_bf16 v[2:17], v[68:71], v[80:83], v[2:17]
	s_waitcnt lgkmcnt(2)
	v_mfma_f32_32x32x16_bf16 v[2:17], v[88:91], v[92:95], v[2:17]
	s_waitcnt lgkmcnt(0)
	v_mfma_f32_32x32x16_bf16 v[2:17], v[96:99], v[100:103], v[2:17]
	s_waitcnt vmcnt(0)
	ds_write_b128 v225, v[228:231]
	ds_write_b128 v225, v[232:235] offset:1152
	ds_write_b128 v225, v[236:239] offset:2304
	ds_write_b128 v225, v[240:243] offset:3456
	ds_write_b128 v225, v[244:247] offset:4608
	ds_write_b128 v225, v[248:251] offset:5760
	ds_write_b128 v225, v[52:55] offset:6912
	ds_write_b128 v225, v[56:59] offset:8064
	s_waitcnt lgkmcnt(0)
	ds_read_b128 v[60:63], v226
	ds_read_b128 v[64:67], v226 offset:4608
	ds_read_b128 v[68:71], v226 offset:32
	ds_read_b128 v[80:83], v226 offset:4640
	ds_read_b128 v[88:91], v226 offset:64
	ds_read_b128 v[92:95], v226 offset:4672
	ds_read_b128 v[96:99], v226 offset:96
	ds_read_b128 v[100:103], v226 offset:4704
	s_waitcnt lgkmcnt(6)
	v_mfma_f32_32x32x16_bf16 v[2:17], v[60:63], v[64:67], v[2:17]
	s_waitcnt lgkmcnt(4)
	v_mfma_f32_32x32x16_bf16 v[2:17], v[68:71], v[80:83], v[2:17]
	s_waitcnt lgkmcnt(2)
	v_mfma_f32_32x32x16_bf16 v[2:17], v[88:91], v[92:95], v[2:17]
	s_waitcnt lgkmcnt(0)
	v_mfma_f32_32x32x16_bf16 v[2:17], v[96:99], v[100:103], v[2:17]
.Lsk3_end_4:
	s_mov_b32 s24, 0x200
	s_mov_b32 s25, 0
	v_lshl_add_u64 v[58:59], v[20:21], 0, s[24:25]
	v_lshl_add_u64 v[60:61], v[30:31], 0, s[24:25]
	s_movk_i32 s10, 0x100
	s_mov_b64 s[18:19], 0
	s_mov_b64 vcc, exec
	s_nop 10
	ds_write2_b32 v34, v2, v3 offset1:33
	ds_write2_b32 v34, v4, v5 offset0:66 offset1:99
	v_add_u32_e32 v2, 0x400, v34
	ds_write2_b32 v2, v6, v7 offset0:8 offset1:41
	ds_write2_b32 v2, v8, v9 offset0:74 offset1:107
	v_add_u32_e32 v2, 0x800, v34
	ds_write2_b32 v2, v10, v11 offset0:16 offset1:49
	ds_write2_b32 v2, v12, v13 offset0:82 offset1:115
	v_add_u32_e32 v2, 0xc00, v34
	ds_write2_b32 v2, v14, v15 offset0:24 offset1:57
	ds_write2_b32 v2, v16, v17 offset0:90 offset1:123
	s_waitcnt lgkmcnt(0)
	s_barrier
	s_and_saveexec_b64 s[18:19], s[0:1]
	s_cbranch_execz .LBB0_1671
	s_and_b32 s10, s20, 0xe0
	s_and_b32 s20, s20, 0xffffff00
	v_or_b32_e32 v37, s10, v33
	s_ashr_i32 s21, s20, 31
	v_lshl_add_u64 v[2:3], s[20:21], 1, v[26:27]
	v_lshlrev_b32_e32 v18, 1, v37
	v_lshl_add_u64 v[2:3], v[2:3], 0, v[18:19]
	global_load_dwordx4 v[2:5], v[2:3], off
	ds_read2_b32 v[6:7], v35 offset1:1
	ds_read2_b32 v[8:9], v35 offset0:2 offset1:3
	ds_read2_b32 v[10:11], v35 offset0:4 offset1:5
	ds_read2_b32 v[12:13], v35 offset0:6 offset1:7
	v_add_u32_e32 v14, 0x1080, v35
	v_add_u32_e32 v16, 0x2100, v35
	v_add_u32_e32 v38, 0x1088, v35
	v_add_u32_e32 v40, 0x2108, v35
	v_add_u32_e32 v42, 0x3188, v35
	v_add_u32_e32 v44, 0x1090, v35
	v_add_u32_e32 v46, 0x2110, v35
	v_add_u32_e32 v48, 0x3190, v35
	v_add_u32_e32 v50, 0x1098, v35
	v_add_u32_e32 v52, 0x2118, v35
	v_add_u32_e32 v54, 0x3198, v35
	v_add_u32_e32 v18, 0x3180, v35
	ds_read2_b32 v[14:15], v14 offset1:1
	ds_read2_b32 v[16:17], v16 offset1:1
	ds_read2_b32 v[30:31], v18 offset1:1
	ds_read2_b32 v[38:39], v38 offset1:1
	ds_read2_b32 v[40:41], v40 offset1:1
	ds_read2_b32 v[42:43], v42 offset1:1
	ds_read2_b32 v[44:45], v44 offset1:1
	ds_read2_b32 v[46:47], v46 offset1:1
	ds_read2_b32 v[48:49], v48 offset1:1
	ds_read2_b32 v[50:51], v50 offset1:1
	ds_read2_b32 v[52:53], v52 offset1:1
	ds_read2_b32 v[54:55], v54 offset1:1
	s_waitcnt lgkmcnt(14)
	v_pk_add_f32 v[6:7], v[6:7], 0 op_sel_hi:[1,0]
	v_pk_add_f32 v[8:9], v[8:9], 0 op_sel_hi:[1,0]
	s_waitcnt lgkmcnt(11)
	v_pk_add_f32 v[6:7], v[6:7], v[14:15]
	v_pk_add_f32 v[10:11], v[10:11], 0 op_sel_hi:[1,0]
	v_pk_add_f32 v[12:13], v[12:13], 0 op_sel_hi:[1,0]
	s_waitcnt lgkmcnt(8)
	v_pk_add_f32 v[8:9], v[8:9], v[38:39]
	v_pk_add_f32 v[6:7], v[6:7], v[16:17]
	s_waitcnt lgkmcnt(5)
	v_pk_add_f32 v[10:11], v[10:11], v[44:45]
	s_waitcnt lgkmcnt(2)
	v_pk_add_f32 v[12:13], v[12:13], v[50:51]
	v_pk_add_f32 v[8:9], v[8:9], v[40:41]
	v_pk_add_f32 v[6:7], v[6:7], v[30:31]
	v_pk_add_f32 v[10:11], v[10:11], v[46:47]
	s_waitcnt lgkmcnt(1)
	v_pk_add_f32 v[12:13], v[12:13], v[52:53]
	v_pk_add_f32 v[8:9], v[8:9], v[42:43]
	v_pk_add_f32 v[10:11], v[10:11], v[48:49]
	s_waitcnt lgkmcnt(0)
	v_pk_add_f32 v[12:13], v[12:13], v[54:55]
	v_and_b32_e32 v57, 64, v36
	v_xor_b32_e32 v56, 1, v36
	v_add_u32_e32 v18, 64, v57
	v_cmp_lt_i32_e32 vcc, v56, v18
	s_waitcnt vmcnt(0)
	v_lshlrev_b32_e32 v14, 16, v2
	v_and_b32_e32 v15, 0xffff0000, v2
	v_lshlrev_b32_e32 v2, 16, v3
	v_and_b32_e32 v3, 0xffff0000, v3
	v_lshlrev_b32_e32 v16, 16, v4
	v_and_b32_e32 v17, 0xffff0000, v4
	v_lshlrev_b32_e32 v30, 16, v5
	v_and_b32_e32 v31, 0xffff0000, v5
	v_pk_add_f32 v[4:5], v[6:7], v[14:15]
	v_pk_add_f32 v[6:7], v[8:9], v[2:3]
	v_pk_mul_f32 v[2:3], v[4:5], v[4:5]
	v_pk_add_f32 v[8:9], v[10:11], v[16:17]
	v_pk_add_f32 v[10:11], v[12:13], v[30:31]
	v_pk_mul_f32 v[12:13], v[6:7], v[6:7]
	v_add_f32_e32 v2, v2, v3
	v_add_f32_e32 v2, v12, v2
	v_pk_mul_f32 v[14:15], v[8:9], v[8:9]
	v_add_f32_e32 v2, v13, v2
	v_add_f32_e32 v2, v14, v2
	v_pk_mul_f32 v[16:17], v[10:11], v[10:11]
	v_add_f32_e32 v2, v15, v2
	v_cndmask_b32_e32 v56, v36, v56, vcc
	v_add_f32_e32 v2, v16, v2
	v_lshlrev_b32_e32 v56, 2, v56
	v_add_f32_e32 v2, v17, v2
	ds_bpermute_b32 v3, v56, v2
	v_xor_b32_e32 v14, 2, v36
	v_cmp_lt_i32_e32 vcc, v14, v18
	v_lshl_add_u64 v[12:13], s[20:21], 2, v[28:29]
	v_lshlrev_b32_e32 v18, 2, v37
	v_cndmask_b32_e32 v14, v36, v14, vcc
	s_waitcnt lgkmcnt(0)
	v_add_f32_e32 v2, v2, v3
	v_lshlrev_b32_e32 v3, 2, v14
	ds_bpermute_b32 v3, v3, v2
	v_lshl_add_u64 v[12:13], v[12:13], 0, v[18:19]
	global_store_dwordx4 v[12:13], v[4:7], off
	global_store_dwordx4 v[12:13], v[8:11], off offset:16
	s_and_b64 exec, exec, s[8:9]
	s_cbranch_execz .LBB0_1671
	s_waitcnt lgkmcnt(0)
	v_add_f32_e32 v2, v2, v3
	global_atomic_add_f32 v[24:25], v2, off
	s_branch .LBB0_1671

.LBB0_1735:
	global_load_dword v2, v1, s[2:3] sc1
	s_mov_b64 s[4:5], -1
	s_waitcnt vmcnt(0)
	v_cmp_lt_u32_e32 vcc, 0x7f, v2
	s_cbranch_vccnz .LBB0_1734
	s_sleep 1
	global_load_dword v2, v1, s[2:3] sc1
	s_waitcnt vmcnt(0)
	v_cmp_gt_u32_e32 vcc, 0x80, v2
	s_cbranch_vccz .LBB0_1734
	s_sleep 1
	global_load_dword v2, v1, s[2:3] sc1
	s_waitcnt vmcnt(0)
	v_cmp_gt_u32_e32 vcc, 0x80, v2
	s_cbranch_vccz .LBB0_1734
	s_sleep 1
	global_load_dword v2, v1, s[2:3] sc1
	s_waitcnt vmcnt(0)
	v_cmp_gt_u32_e32 vcc, 0x80, v2
	s_cbranch_vccz .LBB0_1734
	s_sleep 1
	global_load_dword v2, v1, s[2:3] sc1
	s_waitcnt vmcnt(0)
	v_cmp_gt_u32_e32 vcc, 0x80, v2
	s_cbranch_vccz .LBB0_1734
	s_add_i32 s6, s6, -5
	s_cmp_eq_u32 s6, 0
	s_cselect_b64 s[4:5], -1, 0
	s_sleep 1
	s_branch .LBB0_1734

.LBB0_1742:
	s_or_b64 exec, exec, s[0:1]
	v_lshrrev_b32_e32 v1, 7, v0
	s_and_b32 s0, s94, 1
	v_cmp_eq_u32_e32 vcc, s0, v1
	s_barrier
	s_and_saveexec_b64 s[0:1], vcc
	s_cbranch_execz .LBB0_1744
	v_lshrrev_b32_e32 v1, 2, v0
	v_or_b32_e32 v3, 0x2000, v1
	v_lshlrev_b32_e32 v1, 2, v3
	global_load_dword v20, v1, s[8:9] sc1
	v_lshlrev_b32_e32 v0, 3, v0
	v_and_b32_e32 v0, 24, v0
	s_lshr_b32 s0, s94, 1
	v_mov_b32_e32 v1, 0
	s_nop 0
	v_lshl_or_b32 v2, s0, 5, v0
	v_lshlrev_b32_e32 v0, 13, v3
	v_ashrrev_i32_e32 v3, 31, v2
	v_lshl_add_u64 v[0:1], s[14:15], 0, v[0:1]
	v_lshlrev_b64 v[8:9], 2, v[2:3]
	v_lshl_add_u64 v[16:17], v[0:1], 0, v[8:9]
	global_load_dwordx4 v[0:3], v[16:17], off
	global_load_dwordx4 v[4:7], v[16:17], off offset:16
	v_lshl_add_u64 v[18:19], s[12:13], 0, v[8:9]
	global_load_dwordx4 v[8:11], v[18:19], off
	global_load_dwordx4 v[12:15], v[18:19], off offset:16
	v_mov_b32_e32 v18, 0x358637bd
	s_mov_b32 s0, 0xf800000
	s_waitcnt vmcnt(4)
	v_fmac_f32_e32 v18, 0x3a000000, v20
	v_mul_f32_e32 v19, 0x4f800000, v18
	v_cmp_gt_f32_e32 vcc, s0, v18
	v_mov_b32_e32 v20, 0x260
	s_nop 0
	v_cndmask_b32_e32 v18, v18, v19, vcc
	v_sqrt_f32_e32 v19, v18
	s_nop 0
	v_add_u32_e32 v21, -1, v19
	v_add_u32_e32 v22, 1, v19
	v_fma_f32 v23, -v21, v19, v18
	v_fma_f32 v24, -v22, v19, v18
	v_cmp_ge_f32_e64 s[0:1], 0, v23
	s_nop 1
	v_cndmask_b32_e64 v19, v19, v21, s[0:1]
	v_cmp_lt_f32_e64 s[0:1], 0, v24
	s_nop 1
	v_cndmask_b32_e64 v19, v19, v22, s[0:1]
	v_mul_f32_e32 v21, 0x37800000, v19
	v_cndmask_b32_e32 v19, v19, v21, vcc
	v_cmp_class_f32_e32 vcc, v18, v20
	s_nop 1
	v_cndmask_b32_e32 v18, v19, v18, vcc
	v_div_scale_f32 v19, s[0:1], v18, v18, 1.0
	v_rcp_f32_e32 v20, v19
	v_div_scale_f32 v21, vcc, 1.0, v18, 1.0
	v_fma_f32 v22, -v19, v20, 1.0
	v_fmac_f32_e32 v20, v22, v20
	v_mul_f32_e32 v22, v21, v20
	v_fma_f32 v23, -v19, v22, v21
	v_fmac_f32_e32 v22, v23, v20
	v_fma_f32 v19, -v19, v22, v21
	v_div_fmas_f32 v19, v19, v20, v22
	v_div_fixup_f32 v18, v19, v18, 1.0
	s_waitcnt vmcnt(3)
	v_pk_mul_f32 v[0:1], v[0:1], v[18:19] op_sel_hi:[1,0]
	v_pk_mul_f32 v[2:3], v[2:3], v[18:19] op_sel_hi:[1,0]
	s_waitcnt vmcnt(2)
	v_pk_mul_f32 v[4:5], v[4:5], v[18:19] op_sel_hi:[1,0]
	v_pk_mul_f32 v[6:7], v[6:7], v[18:19] op_sel_hi:[1,0]
	s_waitcnt vmcnt(1)
	v_pk_mul_f32 v[2:3], v[10:11], v[2:3]
	v_pk_mul_f32 v[0:1], v[8:9], v[0:1]
	s_waitcnt vmcnt(0)
	v_pk_mul_f32 v[6:7], v[14:15], v[6:7]
	v_pk_mul_f32 v[4:5], v[12:13], v[4:5]
	global_store_dwordx4 v[16:17], v[0:3], off
	global_store_dwordx4 v[16:17], v[4:7], off offset:16
